# SSD chunk-scan staging: per-piece source select rewritten branch-free (scalar cselect) replacing the compiler's branch tree; on top of EpiResid load hoist
# speedup vs baseline: 1.0165x; 1.0033x over previous
.LBB0_1653:
	s_or_b64 exec, exec, s[42:43]
	s_mul_i32 s2, s76, 0x19800
	s_add_u32 s2, s92, s2
	s_addc_u32 s3, s22, 0
	v_readlane_b32 s6, v253, 4
	s_add_u32 s2, s2, s6
	s_addc_u32 s44, s3, 0
	s_xor_b32 s65, s5, 1
	s_andn2_b64 vcc, exec, s[48:49]
	s_mul_i32 s65, s65, 0x11000
	s_sub_i32 s7, 0x8800, s6
	s_cmp_lt_u32 s33, 0x8800
	s_cselect_b32 s3, 0x4400, s7
	s_cmp_lt_u32 s33, 0x4400
	s_cselect_b32 s3, 0, s3
	s_add_u32 s42, s2, s33
	s_addc_u32 s43, s44, 0
	s_add_u32 s42, s42, s3
	s_addc_u32 s43, s43, 0
	s_add_i32 m0, s8, s65
	v_lshl_add_u64 v[2:3], s[42:43], 0, v[90:91]
	global_load_lds_dwordx4 v[2:3], off
	s_cmp_lt_u32 s25, 0x8800
	s_cselect_b32 s3, 0x4400, s7
	s_cmp_lt_u32 s25, 0x4400
	s_cselect_b32 s3, 0, s3
	s_add_u32 s42, s2, s25
	s_addc_u32 s43, s44, 0
	s_add_u32 s42, s42, s3
	s_addc_u32 s43, s43, 0
	s_add_i32 m0, s9, s65
	v_lshl_add_u64 v[2:3], s[42:43], 0, v[90:91]
	global_load_lds_dwordx4 v[2:3], off
	s_cmp_lt_u32 s70, 0x8800
	s_cselect_b32 s3, 0x4400, s7
	s_cmp_lt_u32 s70, 0x4400
	s_cselect_b32 s3, 0, s3
	s_add_u32 s42, s2, s70
	s_addc_u32 s43, s44, 0
	s_add_u32 s42, s42, s3
	s_addc_u32 s43, s43, 0
	s_add_i32 m0, s84, s65
	v_lshl_add_u64 v[2:3], s[42:43], 0, v[90:91]
	global_load_lds_dwordx4 v[2:3], off
	s_cmp_lt_u32 s96, 0x8800
	s_cselect_b32 s3, 0x4400, s7
	s_cmp_lt_u32 s96, 0x4400
	s_cselect_b32 s3, 0, s3
	s_add_u32 s42, s2, s96
	s_addc_u32 s43, s44, 0
	s_add_u32 s42, s42, s3
	s_addc_u32 s43, s43, 0
	s_add_i32 m0, s85, s65
	v_lshl_add_u64 v[2:3], s[42:43], 0, v[90:91]
	global_load_lds_dwordx4 v[2:3], off
	s_cmp_lt_u32 s97, 0x8800
	s_cselect_b32 s3, 0x4400, s7
	s_cmp_lt_u32 s97, 0x4400
	s_cselect_b32 s3, 0, s3
	s_add_u32 s42, s2, s97
	s_addc_u32 s43, s44, 0
	s_add_u32 s42, s42, s3
	s_addc_u32 s43, s43, 0
	s_add_i32 m0, s68, s65
	v_lshl_add_u64 v[2:3], s[42:43], 0, v[90:91]
	global_load_lds_dwordx4 v[2:3], off
	s_cmp_lt_u32 s12, 0x8800
	s_cselect_b32 s3, 0x4400, s7
	s_cmp_lt_u32 s12, 0x4400
	s_cselect_b32 s3, 0, s3
	s_add_u32 s42, s2, s12
	s_addc_u32 s43, s44, 0
	s_add_u32 s42, s42, s3
	s_addc_u32 s43, s43, 0
	s_add_i32 m0, s69, s65
	v_lshl_add_u64 v[2:3], s[42:43], 0, v[90:91]
	global_load_lds_dwordx4 v[2:3], off
	s_cmp_lt_u32 s13, 0x8800
	s_cselect_b32 s3, 0x4400, s7
	s_cmp_lt_u32 s13, 0x4400
	s_cselect_b32 s3, 0, s3
	s_add_u32 s42, s2, s13
	s_addc_u32 s43, s44, 0
	s_add_u32 s42, s42, s3
	s_addc_u32 s43, s43, 0
	s_add_i32 m0, s14, s65
	v_lshl_add_u64 v[2:3], s[42:43], 0, v[90:91]
	global_load_lds_dwordx4 v[2:3], off
	s_cmp_lt_u32 s28, 0x8800
	s_cselect_b32 s3, 0x4400, s7
	s_cmp_lt_u32 s28, 0x4400
	s_cselect_b32 s3, 0, s3
	s_add_u32 s42, s2, s28
	s_addc_u32 s43, s44, 0
	s_add_u32 s42, s42, s3
	s_addc_u32 s43, s43, 0
	s_add_i32 m0, s15, s65
	v_lshl_add_u64 v[2:3], s[42:43], 0, v[90:91]
	global_load_lds_dwordx4 v[2:3], off
	s_andn2_b64 vcc, exec, s[66:67]
	s_cbranch_vccnz .LBB0_1744
	s_cmp_lt_u32 s29, 0x8800
	s_cselect_b32 s3, 0x4400, s7
	s_cmp_lt_u32 s29, 0x4400
	s_cselect_b32 s3, 0, s3
	s_add_u32 s42, s2, s29
	s_addc_u32 s43, s44, 0
	s_add_u32 s42, s42, s3
	s_addc_u32 s43, s43, 0
	s_add_i32 m0, s0, s65
	v_lshl_add_u64 v[2:3], s[42:43], 0, v[90:91]
	global_load_lds_dwordx4 v[2:3], off
	s_branch .LBB0_1744
.LBB0_1694:
	v_mov_b32_e32 v99, v15
	v_mov_b32_e32 v98, v14
	v_mov_b32_e32 v101, v13
	v_mov_b32_e32 v100, v12
	v_mov_b32_e32 v103, v19
	v_mov_b32_e32 v102, v18
	v_mov_b32_e32 v105, v17
	v_mov_b32_e32 v104, v16
	v_mov_b32_e32 v107, v23
	v_mov_b32_e32 v106, v22
	v_mov_b32_e32 v109, v21
	v_mov_b32_e32 v108, v20
	v_mov_b32_e32 v111, v27
	v_mov_b32_e32 v110, v26
	v_mov_b32_e32 v113, v25
	v_mov_b32_e32 v112, v24
.LBB0_1744:
	s_mul_i32 s2, s5, 0x11000
	s_add_i32 s2, s2, 0
	s_add_i32 s3, s23, s2
	v_add3_u32 v10, s3, v128, v88
	v_add_u32_e32 v44, 0x4000, v10
	v_cvt_pk_bf16_f32 v2, v28, v29
	v_cvt_pk_bf16_f32 v3, v30, v31
	v_cvt_pk_bf16_f32 v4, v32, v33
	v_cvt_pk_bf16_f32 v5, v34, v35
	ds_read2_b64 v[6:9], v44 offset0:128 offset1:132
	v_cvt_pk_bf16_f32 v48, v36, v37
	v_cvt_pk_bf16_f32 v49, v38, v39
	v_cvt_pk_bf16_f32 v50, v40, v41
	v_cvt_pk_bf16_f32 v51, v42, v43
	ds_read2_b64 v[44:47], v44 offset0:136 offset1:140
	s_waitcnt lgkmcnt(0)
	v_mfma_f32_16x16x32_bf16 v[6:9], v[2:5], v[6:9], 0
	s_lshl_b32 s5, s5, 10
	s_add_i32 s65, s5, 0
	s_add_i32 s65, s65, 0x22000
	v_mfma_f32_16x16x32_bf16 v[52:55], v[48:51], v[44:47], v[6:9]
	v_add_u32_e32 v44, 0x5000, v10
	v_add_u32_e32 v114, s2, v88
	v_lshl_add_u32 v182, v115, 2, s65
	s_nop 0
	ds_read2_b64 v[6:9], v44 offset0:160 offset1:164
	ds_read2_b64 v[44:47], v44 offset0:168 offset1:172
	s_waitcnt lgkmcnt(0)
	v_mfma_f32_16x16x32_bf16 v[6:9], v[2:5], v[6:9], 0
	s_mov_b64 s[42:43], -1
	s_andn2_b64 vcc, exec, s[10:11]
	v_mfma_f32_16x16x32_bf16 v[56:59], v[48:51], v[44:47], v[6:9]
	v_add_u32_e32 v44, 0x6000, v10
	v_add_u32_e32 v10, 0x7000, v10
	ds_read2_b64 v[60:63], v10 offset0:224 offset1:228
	s_nop 1
	ds_read2_b64 v[6:9], v44 offset0:192 offset1:196
	ds_read2_b64 v[44:47], v44 offset0:200 offset1:204
	s_waitcnt lgkmcnt(0)
	v_mfma_f32_16x16x32_bf16 v[6:9], v[2:5], v[6:9], 0
	v_mfma_f32_16x16x32_bf16 v[44:47], v[48:51], v[44:47], v[6:9]
	s_nop 6
	ds_read2_b64 v[6:9], v10 offset0:232 offset1:236
	v_mfma_f32_16x16x32_bf16 v[2:5], v[2:5], v[60:63], 0
	v_mov_b32_e32 v10, s65
	ds_read_b32 v181, v10 offset:508
	s_waitcnt lgkmcnt(0)
	v_mfma_f32_16x16x32_bf16 v[48:51], v[48:51], v[6:9], v[2:5]
	v_add_u32_e32 v6, s35, v127
	s_nop 2
	v_cndmask_b32_e64 v5, v59, v55, s[40:41]
	v_cndmask_b32_e64 v4, v58, v54, s[40:41]
	v_cndmask_b32_e64 v3, v57, v53, s[40:41]
	v_cndmask_b32_e64 v2, v56, v52, s[40:41]
	ds_write_b128 v6, v[2:5]
	v_cndmask_b32_e64 v5, v47, v51, s[40:41]
	v_cndmask_b32_e64 v4, v46, v50, s[40:41]
	v_cndmask_b32_e64 v3, v45, v49, s[40:41]
	v_cndmask_b32_e64 v2, v44, v48, s[40:41]
	ds_write_b128 v176, v[2:5] offset:1024
	v_mov_b32_e32 v2, v177
	s_waitcnt lgkmcnt(0)
	s_barrier
	s_nop 0
	v_and_b32_e32 v10, 15, v2
	v_or_b32_e32 v86, s18, v10
	v_lshl_add_u32 v3, v86, 2, s65
	v_mad_u64_u32 v[6:7], s[2:3], v2, s71, v[114:115]
	ds_read2st64_b32 v[76:77], v3 offset1:2
	ds_read2_b64 v[2:5], v6 offset1:4
	ds_read2_b64 v[64:67], v6 offset0:8 offset1:12
	ds_read_b128 v[60:63], v178
	ds_read_b128 v[72:75], v182
	ds_read_b128 v[68:71], v182 offset:64
	s_waitcnt lgkmcnt(0)
	v_lshlrev_b32_e32 v84, 16, v2
	v_and_b32_e32 v85, 0xffff0000, v2
	v_lshlrev_b32_e32 v82, 16, v3
	v_and_b32_e32 v83, 0xffff0000, v3
	v_lshlrev_b32_e32 v80, 16, v4
	v_and_b32_e32 v81, 0xffff0000, v4
	v_lshlrev_b32_e32 v78, 16, v5
	v_and_b32_e32 v79, 0xffff0000, v5
	s_cbranch_vccnz .LBB0_1746
	v_sub_f32_e32 v2, v76, v72
	v_sub_f32_e32 v3, v76, v73
	v_sub_f32_e32 v4, v76, v74
	v_sub_f32_e32 v5, v76, v75
	v_sub_f32_e32 v6, v76, v68
	v_sub_f32_e32 v7, v76, v69
	v_sub_f32_e32 v8, v76, v70
	v_sub_f32_e32 v9, v76, v71
	v_exp_f32_e32 v2, v2
	v_exp_f32_e32 v3, v3
	v_exp_f32_e32 v4, v4
	v_exp_f32_e32 v5, v5
	v_exp_f32_e32 v6, v6
	v_exp_f32_e32 v8, v8
	v_exp_f32_e32 v9, v9
	v_exp_f32_e32 v7, v7
	v_pk_mul_f32 v[2:3], v[2:3], v[84:85]
	v_pk_mul_f32 v[4:5], v[4:5], v[82:83]
	v_pk_mul_f32 v[8:9], v[8:9], v[78:79]
	v_pk_mul_f32 v[6:7], v[6:7], v[80:81]
	s_mov_b64 s[42:43], 0
